# M1: the 64 RG-LRU sample-row units moved from workgroups 0-63 to 192-255 so they no longer share workgroups with the extra RWKV pre-pass units
# speedup vs baseline: 1.0113x; 1.0001x over previous
; #define LAS __attribute__((address_space(3)))
; __device__ __forceinline__ void phase_m1(PP P, int l, LAS unsigned char* lds, const Ids I) {
;     ...
;         for (int u = BID; u < 264 * 8; u += NB) {
;             const int tt = u >> 3, n = u & 7, r0 = tt * 64, chg = n * 64 + d;
;             if (u == BID || (NB & 7) != 0) {
;     ...
; #pragma unroll
;             for (int i = 0; i < 2; ++i) { const int idx = tid + 512 * i, a = idx >> 9, rem = idx & 511, tok = rem >> 3, c8 = (rem & 7) * 8;
;                 *(u32x4*)(arr + (a == 0 ? A_LA : A_GX) * AS + (size_t)(r0 + tok) * 512 + n * 64 + c8) = *(const LAS u32x4*)(OB + a * 4096 + tok * 64 + c8); }
;             __syncthreads();
.LBB0_91:
	v_or_b32_e32 v32, s25, v69
	v_ashrrev_i32_e32 v33, 31, v32
	v_lshlrev_b64 v[32:33], 10, v[32:33]
	v_lshl_add_u64 v[32:33], s[96:97], 0, v[32:33]
	s_lshl_b32 s54, s3, 1
	v_lshl_add_u64 v[32:33], v[32:33], 0, s[54:55]
	v_mov_b32_e32 v55, v145
	s_waitcnt lgkmcnt(0)
	s_barrier
	v_lshl_add_u64 v[36:37], v[32:33], 0, v[54:55]
	ds_read_b128 v[32:35], v80 offset:26624
	v_mov_b32_e32 v57, v145
	v_lshl_add_u64 v[38:39], v[36:37], 0, v[56:57]
	v_mov_b32_e32 v59, v145
	s_add_i32 s1, s1, s72
	s_waitcnt lgkmcnt(0)
	global_store_dwordx4 v[38:39], v[32:35], off
	ds_read_b128 v[32:35], v80 offset:34816
	s_add_i32 s22, s22, s72
	s_add_i32 s0, s0, s44
	v_lshl_add_u64 v[36:37], v[36:37], 0, v[58:59]
	s_cmpk_lt_i32 s1, 0x800
	s_cbranch_scc1 .Lp1b_c
	s_sub_i32 s4, s1, 0x8c0
	s_cmp_lt_u32 s4, 64
	s_cbranch_scc0 .Lp1b_x
	s_sub_i32 s0, s0, 0x600
.Lp1b_c:
	s_cmp_lg_u32 s0, s0
	s_branch .Lp1b_d
.Lp1b_x:
	s_cmp_eq_u32 s0, s0
.Lp1b_d:
	s_nop 0
	s_nop 0
	s_nop 0
	s_nop 0
	s_nop 0
	s_nop 0
	s_nop 0
	s_waitcnt lgkmcnt(0)
	global_store_dwordx4 v[36:37], v[32:35], off
	s_barrier
	s_cbranch_scc1 .LBB0_224

; __device__ __forceinline__ float bf2f(bf16_t h) { return __uint_as_float((unsigned)h << 16); }
; __device__ __forceinline__ bf16_t f2bf(float f) { return (bf16_t)(cvt_pk_bf16(f, 0.f) & 0xffffu); }
; __device__ __forceinline__ void phase_m1(PP P, int l, LAS unsigned char* lds, const Ids I) {
;     ...
;             for (int i = 0; i < 8; ++i) { const int r = r0 + tg * 8 + i, t = t_in_seq(r); float a = cb;
; #pragma unroll
;                 for (int j = 0; j < 4; ++j) { const int ts = t - 3 + j; float xv;
;                     if (ts >= 0) xv = bf2f(PR[(size_t)(r - 3 + j) * INW + chg]);
;                     else xv = (r < MTP) ? 0.f : P->in[I_SCONV][(((size_t)l * 128 + ((r - MTP) >> 2)) * 3 + (ts + 3)) * 512 + chg];
;                     a += xv * cwv[j]; }
;                 XC[d * 68 + tg * 8 + i] = a; XB[(tg * 8 + i) * 72 + d] = f2bf(a); }
.Lcv_fma:
	v_fma_f32 v130, v153, v116, v156
	v_fmac_f32_e32 v130, v152, v117
	v_fmac_f32_e32 v130, v154, v118
	v_fmac_f32_e32 v130, v155, v119
	v_fma_f32 v131, v153, v117, v156
	v_fmac_f32_e32 v131, v152, v118
	v_fmac_f32_e32 v131, v154, v119
	v_fmac_f32_e32 v131, v155, v120
	v_fma_f32 v132, v153, v118, v156
	v_fmac_f32_e32 v132, v152, v119
	v_fmac_f32_e32 v132, v154, v120
	v_fmac_f32_e32 v132, v155, v121
	v_fma_f32 v133, v153, v119, v156
	v_fmac_f32_e32 v133, v152, v120
	v_fmac_f32_e32 v133, v154, v121
	v_fmac_f32_e32 v133, v155, v122
	v_fma_f32 v134, v153, v123, v156
	v_fmac_f32_e32 v134, v152, v124
	v_fmac_f32_e32 v134, v154, v125
	v_fmac_f32_e32 v134, v155, v126
	v_fma_f32 v135, v153, v124, v156
	v_fmac_f32_e32 v135, v152, v125
	v_fmac_f32_e32 v135, v154, v126
	v_fmac_f32_e32 v135, v155, v127
	v_fma_f32 v136, v153, v125, v156
	v_fmac_f32_e32 v136, v152, v126
	v_fmac_f32_e32 v136, v154, v127
	v_fmac_f32_e32 v136, v155, v128
	v_fma_f32 v137, v153, v126, v156
	v_fmac_f32_e32 v137, v152, v127
	v_fmac_f32_e32 v137, v154, v128
	v_fmac_f32_e32 v137, v155, v129
	s_add_i32 s18, s1, s72
	s_add_i32 s19, s0, s44
	s_cmpk_lt_i32 s18, 0x800
	s_cbranch_scc1 .Lcv_pf_go
	s_sub_i32 s18, s18, 0x8c0
	s_cmp_lt_u32 s18, 64
	s_cbranch_scc0 .Lcv_pf_done
	s_sub_i32 s19, s19, 0x600
.Lcv_pf_go:
	s_nop 0
	s_and_b32 s18, s19, 0xffffffc0
	s_lshr_b32 s4, s62, 3
	s_add_i32 s100, s18, s4
	v_or_b32_e32 v142, s3, v66
	v_lshlrev_b32_e32 v143, 2, v142
	v_lshlrev_b32_e32 v142, 1, v142
	s_cmp_ge_i32 s100, s91
	s_cbranch_scc1 .Lcv_ld_sample_b
	s_add_i32 s18, s100, -3
	s_mul_hi_i32 s19, s18, s73
	s_mul_i32 s18, s18, s73
	s_add_u32 s18, s60, s18
	s_addc_u32 s19, s61, s19
	global_load_ushort v116, v142, s[18:19]
	s_add_u32 s18, s18, 0x1600
	s_addc_u32 s19, s19, 0
	global_load_ushort v117, v142, s[18:19]
	s_add_u32 s18, s18, 0x1600
	s_addc_u32 s19, s19, 0
	global_load_ushort v118, v142, s[18:19]
	s_add_u32 s18, s18, 0x1600
	s_addc_u32 s19, s19, 0
	global_load_ushort v119, v142, s[18:19]
	s_add_u32 s18, s18, 0x1600
	s_addc_u32 s19, s19, 0
	global_load_ushort v120, v142, s[18:19]
	s_add_u32 s18, s18, 0x1600
	s_addc_u32 s19, s19, 0
	global_load_ushort v121, v142, s[18:19]
	s_add_u32 s18, s18, 0x1600
	s_addc_u32 s19, s19, 0
	global_load_ushort v122, v142, s[18:19]
	s_add_u32 s18, s18, 0x1600
	s_addc_u32 s19, s19, 0
	global_load_ushort v126, v142, s[18:19]
	s_add_u32 s18, s18, 0x1600
	s_addc_u32 s19, s19, 0
	global_load_ushort v127, v142, s[18:19]
	s_add_u32 s18, s18, 0x1600
	s_addc_u32 s19, s19, 0
	global_load_ushort v128, v142, s[18:19]
	s_add_u32 s18, s18, 0x1600
	s_addc_u32 s19, s19, 0
	global_load_ushort v129, v142, s[18:19]
	s_branch .Lcv_ld_done_b
